# row-norm phases (7, 10, 16, 19): next trip's rows prefetched into L2 by loads into unused registers; counted waits +8
# baseline (speedup 1.0000x reference)
; DI void phase_rmsnorm(const Ctx& c, const float* src, const float* w) {
;     ...
;   for (int u = blockIdx.x; u < NTOK / 8; u += gridDim.x) {
;     const int row = u * 8 + wid * 2;
;     const float* xr = src + (size_t)row * 1024;
;     f32x4 v[2][4];
; #pragma unroll
;     for (int r = 0; r < 2; ++r)
; #pragma unroll
;       for (int i = 0; i < 4; ++i) v[r][i] = *(const f32x4*)(xr + r * 1024 + i * 256 + lane * 4);
; #pragma unroll
;     for (int r = 0; r < 2; ++r) {
;       float ss = 0.f;
; #pragma unroll
;       for (int i = 0; i < 4; ++i) ss += v[r][i][0] * v[r][i][0] + v[r][i][1] * v[r][i][1] + v[r][i][2] * v[r][i][2] + v[r][i][3] * v[r][i][3];
;       ss = wave_sum(ss);
.LBB0_886:
	v_ashrrev_i32_e32 v33, 31, v32
	v_lshlrev_b64 v[16:17], 12, v[32:33]
	v_lshl_add_u64 v[16:17], v[28:29], 0, v[16:17]
	global_load_dwordx4 v[38:41], v[16:17], off
	global_load_dwordx4 v[42:45], v[16:17], off offset:1024
	global_load_dwordx4 v[46:49], v[16:17], off offset:2048
	global_load_dwordx4 v[50:53], v[16:17], off offset:3072
	v_add_co_u32_e32 v16, vcc, 0x1000, v16
	s_add_i32 s4, s4, s1
	s_nop 0
	v_addc_co_u32_e32 v17, vcc, 0, v17, vcc
	global_load_dwordx4 v[54:57], v[16:17], off
	global_load_dwordx4 v[24:27], v[16:17], off offset:1024
	global_load_dwordx4 v[20:23], v[16:17], off offset:2048
	s_nop 0
	global_load_dwordx4 v[16:19], v[16:17], off offset:3072
	v_add_u32_e32 v200, s2, v32
	v_min_u32_e32 v200, 0x7ffe, v200
	v_mov_b32_e32 v201, 0
	v_lshlrev_b64 v[202:203], 12, v[200:201]
	v_lshl_add_u64 v[202:203], v[28:29], 0, v[202:203]
	global_load_dwordx4 v[204:207], v[202:203], off
	global_load_dwordx4 v[208:211], v[202:203], off offset:1024
	global_load_dwordx4 v[212:215], v[202:203], off offset:2048
	global_load_dwordx4 v[216:219], v[202:203], off offset:3072
	v_add_co_u32_e32 v202, vcc, 0x1000, v202
	s_nop 1
	v_addc_co_u32_e32 v203, vcc, 0, v203, vcc
	global_load_dwordx4 v[220:223], v[202:203], off
	global_load_dwordx4 v[224:227], v[202:203], off offset:1024
	global_load_dwordx4 v[228:231], v[202:203], off offset:2048
	global_load_dwordx4 v[232:235], v[202:203], off offset:3072
	s_cmpk_lt_i32 s4, 0x1000
	s_waitcnt vmcnt(15)
	v_mov_b32_e32 v60, v39
	s_waitcnt vmcnt(14)
	v_mov_b32_e32 v61, v43
	s_waitcnt vmcnt(13)
	v_mov_b32_e32 v68, v47
	s_waitcnt vmcnt(12)
	v_mov_b32_e32 v69, v51
	v_mov_b32_e32 v58, v38
	v_mov_b32_e32 v59, v42
	v_mov_b32_e32 v66, v46
	v_mov_b32_e32 v67, v50
	v_pk_mul_f32 v[60:61], v[60:61], v[60:61]
	v_pk_mul_f32 v[68:69], v[68:69], v[68:69]
	v_mov_b32_e32 v62, v40
	v_mov_b32_e32 v63, v44
	v_pk_fma_f32 v[58:59], v[58:59], v[58:59], v[60:61]
	v_pk_fma_f32 v[60:61], v[66:67], v[66:67], v[68:69]
	s_waitcnt vmcnt(11)
	v_mov_b32_e32 v68, v55
	s_waitcnt vmcnt(10)
	v_mov_b32_e32 v69, v25
	v_mov_b32_e32 v66, v54
	v_mov_b32_e32 v67, v24
	s_waitcnt vmcnt(9)
	v_mov_b32_e32 v80, v21
	s_waitcnt vmcnt(8)
	v_mov_b32_e32 v81, v17
	v_pk_fma_f32 v[58:59], v[62:63], v[62:63], v[58:59]
	v_pk_mul_f32 v[62:63], v[68:69], v[68:69]
	v_mov_b32_e32 v64, v41
	v_mov_b32_e32 v65, v45
	v_mov_b32_e32 v74, v56
	v_mov_b32_e32 v75, v26
	v_mov_b32_e32 v78, v20
	v_mov_b32_e32 v79, v16
	v_pk_mul_f32 v[68:69], v[80:81], v[80:81]
	v_pk_fma_f32 v[62:63], v[66:67], v[66:67], v[62:63]
	v_mov_b32_e32 v70, v48
	v_mov_b32_e32 v71, v52
	v_mov_b32_e32 v76, v57
	v_mov_b32_e32 v77, v27
	v_mov_b32_e32 v82, v22
	v_mov_b32_e32 v83, v18
	v_pk_fma_f32 v[58:59], v[64:65], v[64:65], v[58:59]
	v_pk_fma_f32 v[64:65], v[78:79], v[78:79], v[68:69]
	v_pk_fma_f32 v[62:63], v[74:75], v[74:75], v[62:63]
	v_mov_b32_e32 v72, v49
	v_mov_b32_e32 v73, v53
	v_mov_b32_e32 v84, v23
	v_mov_b32_e32 v85, v19
	v_pk_fma_f32 v[60:61], v[70:71], v[70:71], v[60:61]
	v_pk_fma_f32 v[64:65], v[82:83], v[82:83], v[64:65]
	v_pk_fma_f32 v[62:63], v[76:77], v[76:77], v[62:63]
	v_pk_fma_f32 v[60:61], v[72:73], v[72:73], v[60:61]
	v_mov_b32_e32 v67, v58
	v_pk_fma_f32 v[64:65], v[84:85], v[84:85], v[64:65]
	v_mov_b32_e32 v66, v62
	v_mov_b32_e32 v58, v63
	v_mov_b32_e32 v69, v60
	v_mov_b32_e32 v68, v64
	v_pk_add_f32 v[58:59], v[66:67], v[58:59]
	v_mov_b32_e32 v60, v65
	v_pk_add_f32 v[58:59], v[58:59], v[68:69]
	s_nop 0
	v_pk_add_f32 v[58:59], v[58:59], v[60:61]
	s_nop 1
	v_mov_b32_dpp v61, v59 quad_perm:[1,0,3,2] row_mask:0xf bank_mask:0xf bound_ctrl:1
	v_mov_b32_dpp v60, v58 quad_perm:[1,0,3,2] row_mask:0xf bank_mask:0xf bound_ctrl:1
	v_pk_add_f32 v[58:59], v[58:59], v[60:61]
	s_nop 1
	v_mov_b32_dpp v61, v59 quad_perm:[2,3,0,1] row_mask:0xf bank_mask:0xf bound_ctrl:1
	v_mov_b32_dpp v60, v58 quad_perm:[2,3,0,1] row_mask:0xf bank_mask:0xf bound_ctrl:1
	v_pk_add_f32 v[58:59], v[58:59], v[60:61]
	s_nop 1
	v_mov_b32_dpp v61, v59 row_half_mirror row_mask:0xf bank_mask:0xf bound_ctrl:1
	v_mov_b32_dpp v60, v58 row_half_mirror row_mask:0xf bank_mask:0xf bound_ctrl:1
	v_pk_add_f32 v[58:59], v[58:59], v[60:61]
	s_nop 1
	v_mov_b32_dpp v61, v59 row_mirror row_mask:0xf bank_mask:0xf bound_ctrl:1
	v_mov_b32_dpp v60, v58 row_mirror row_mask:0xf bank_mask:0xf bound_ctrl:1
	v_pk_add_f32 v[58:59], v[58:59], v[60:61]
	ds_bpermute_b32 v61, v36, v59
	ds_bpermute_b32 v60, v36, v58
	s_waitcnt lgkmcnt(0)
; DI unsigned pack2(float lo, float hi) { const f32x2c v = {lo, hi}; return __builtin_bit_cast(unsigned, __builtin_convertvector(v, bf16x2c)); }
; DI void phase_rmsnorm(const Ctx& c, const float* src, const float* w) {
;     ...
;       ss = wave_sum(ss);
;       const float rs = rsqrtf(ss * (1.0f / 1024.0f) + 1e-5f);
;       bf16_t* o = xn + (size_t)(row + r) * 1024;
; #pragma unroll
;       for (int i = 0; i < 4; ++i) { u32x2 q; q.x = pack2(v[r][i][0] * rs * g[i][0], v[r][i][1] * rs * g[i][1]); q.y = pack2(v[r][i][2] * rs * g[i][2], v[r][i][3] * rs * g[i][3]); *(u32x2*)(o + i * 256 + lane * 4) = q; }
;     }
	v_pk_add_f32 v[58:59], v[58:59], v[60:61]
	ds_bpermute_b32 v61, v37, v59
	ds_bpermute_b32 v60, v37, v58
	s_waitcnt lgkmcnt(0)
	v_pk_add_f32 v[58:59], v[58:59], v[60:61]
	s_nop 0
	v_pk_fma_f32 v[58:59], v[58:59], s[0:1], v[34:35] op_sel_hi:[1,0,0]
	s_nop 0
	v_mul_f32_e32 v60, 0x4b800000, v59
	v_cmp_gt_f32_e32 vcc, s3, v59
	s_nop 1
	v_cndmask_b32_e32 v59, v59, v60, vcc
	v_rsq_f32_e32 v59, v59
	v_lshlrev_b64 v[60:61], 11, v[32:33]
	v_mul_f32_e32 v33, 0x4b800000, v58
	v_lshl_add_u64 v[60:61], v[30:31], 0, v[60:61]
	v_mul_f32_e32 v62, 0x45800000, v59
	v_cndmask_b32_e32 v62, v59, v62, vcc
	v_cmp_gt_f32_e32 vcc, s3, v58
	v_pk_mul_f32 v[38:39], v[38:39], v[62:63] op_sel_hi:[1,0]
	v_pk_mul_f32 v[40:41], v[40:41], v[62:63] op_sel_hi:[1,0]
	v_cndmask_b32_e32 v33, v58, v33, vcc
	v_rsq_f32_e32 v33, v33
	v_pk_mul_f32 v[42:43], v[42:43], v[62:63] op_sel_hi:[1,0]
	v_pk_mul_f32 v[44:45], v[44:45], v[62:63] op_sel_hi:[1,0]
	v_pk_mul_f32 v[46:47], v[46:47], v[62:63] op_sel_hi:[1,0]
	v_pk_mul_f32 v[48:49], v[48:49], v[62:63] op_sel_hi:[1,0]
	v_pk_mul_f32 v[38:39], v[12:13], v[38:39]
	v_pk_mul_f32 v[40:41], v[14:15], v[40:41]
	v_pk_mul_f32 v[52:53], v[52:53], v[62:63] op_sel_hi:[1,0]
	v_pk_mul_f32 v[42:43], v[8:9], v[42:43]
	v_pk_mul_f32 v[44:45], v[10:11], v[44:45]
	v_pk_mul_f32 v[46:47], v[4:5], v[46:47]
	v_pk_mul_f32 v[48:49], v[6:7], v[48:49]
	v_cvt_pk_bf16_f32 v38, v38, v39
	v_cvt_pk_bf16_f32 v39, v40, v41
	v_pk_mul_f32 v[50:51], v[50:51], v[62:63] op_sel_hi:[1,0]
	v_cvt_pk_bf16_f32 v40, v42, v43
	v_cvt_pk_bf16_f32 v41, v44, v45
	v_cvt_pk_bf16_f32 v42, v46, v47
	v_cvt_pk_bf16_f32 v43, v48, v49
	global_store_dwordx2 v[60:61], v[38:39], off
	global_store_dwordx2 v[60:61], v[40:41], off offset:512
	global_store_dwordx2 v[60:61], v[42:43], off offset:1024
	v_pk_mul_f32 v[38:39], v[2:3], v[52:53]
	v_pk_mul_f32 v[50:51], v[0:1], v[50:51]
	v_cvt_pk_bf16_f32 v45, v38, v39
	v_mul_f32_e32 v38, 0x45800000, v33
	v_cvt_pk_bf16_f32 v44, v50, v51
	v_cndmask_b32_e32 v38, v33, v38, vcc
	v_add_u32_e32 v40, 1, v32
	global_store_dwordx2 v[60:61], v[44:45], off offset:1536
	v_ashrrev_i32_e32 v41, 31, v40
	v_pk_mul_f32 v[42:43], v[54:55], v[38:39] op_sel_hi:[1,0]
	v_pk_mul_f32 v[44:45], v[56:57], v[38:39] op_sel_hi:[1,0]
	v_pk_mul_f32 v[24:25], v[24:25], v[38:39] op_sel_hi:[1,0]
	v_pk_mul_f32 v[26:27], v[26:27], v[38:39] op_sel_hi:[1,0]
	v_pk_mul_f32 v[20:21], v[20:21], v[38:39] op_sel_hi:[1,0]
	v_pk_mul_f32 v[22:23], v[22:23], v[38:39] op_sel_hi:[1,0]
	v_pk_mul_f32 v[16:17], v[16:17], v[38:39] op_sel_hi:[1,0]
	v_pk_mul_f32 v[18:19], v[18:19], v[38:39] op_sel_hi:[1,0]
	v_lshlrev_b64 v[40:41], 11, v[40:41]
	v_pk_mul_f32 v[42:43], v[12:13], v[42:43]
	v_pk_mul_f32 v[44:45], v[14:15], v[44:45]
	v_pk_mul_f32 v[24:25], v[8:9], v[24:25]
	v_pk_mul_f32 v[26:27], v[10:11], v[26:27]
	v_pk_mul_f32 v[20:21], v[4:5], v[20:21]
	v_pk_mul_f32 v[22:23], v[6:7], v[22:23]
	v_pk_mul_f32 v[16:17], v[0:1], v[16:17]
	v_pk_mul_f32 v[18:19], v[2:3], v[18:19]
	v_lshl_add_u64 v[40:41], v[30:31], 0, v[40:41]
	v_cvt_pk_bf16_f32 v42, v42, v43
	v_cvt_pk_bf16_f32 v43, v44, v45
	v_cvt_pk_bf16_f32 v24, v24, v25
	v_cvt_pk_bf16_f32 v25, v26, v27
	v_cvt_pk_bf16_f32 v20, v20, v21
	v_cvt_pk_bf16_f32 v21, v22, v23
	v_cvt_pk_bf16_f32 v16, v16, v17
	v_cvt_pk_bf16_f32 v17, v18, v19
	v_add_u32_e32 v32, s2, v32
	global_store_dwordx2 v[40:41], v[42:43], off
	global_store_dwordx2 v[40:41], v[24:25], off offset:512
	global_store_dwordx2 v[40:41], v[20:21], off offset:1024
	global_store_dwordx2 v[40:41], v[16:17], off offset:1536
	s_cbranch_scc1 .LBB0_886

; DI void phase_rmsnorm(const Ctx& c, const float* src, const float* w) {
;     ...
;   for (int u = blockIdx.x; u < NTOK / 8; u += gridDim.x) {
;     const int row = u * 8 + wid * 2;
;     const float* xr = src + (size_t)row * 1024;
;     f32x4 v[2][4];
; #pragma unroll
;     for (int r = 0; r < 2; ++r)
; #pragma unroll
;       for (int i = 0; i < 4; ++i) v[r][i] = *(const f32x4*)(xr + r * 1024 + i * 256 + lane * 4);
; #pragma unroll
;     for (int r = 0; r < 2; ++r) {
;       float ss = 0.f;
; #pragma unroll
;       for (int i = 0; i < 4; ++i) ss += v[r][i][0] * v[r][i][0] + v[r][i][1] * v[r][i][1] + v[r][i][2] * v[r][i][2] + v[r][i][3] * v[r][i][3];
;       ss = wave_sum(ss);
.LBB0_960:
	v_ashrrev_i32_e32 v33, 31, v32
	v_lshlrev_b64 v[16:17], 12, v[32:33]
	v_lshl_add_u64 v[16:17], v[28:29], 0, v[16:17]
	global_load_dwordx4 v[38:41], v[16:17], off
	global_load_dwordx4 v[42:45], v[16:17], off offset:1024
	global_load_dwordx4 v[46:49], v[16:17], off offset:2048
	global_load_dwordx4 v[50:53], v[16:17], off offset:3072
	v_add_co_u32_e32 v16, vcc, 0x1000, v16
	s_add_i32 s4, s4, s1
	s_nop 0
	v_addc_co_u32_e32 v17, vcc, 0, v17, vcc
	global_load_dwordx4 v[54:57], v[16:17], off
	global_load_dwordx4 v[24:27], v[16:17], off offset:1024
	global_load_dwordx4 v[20:23], v[16:17], off offset:2048
	s_nop 0
	global_load_dwordx4 v[16:19], v[16:17], off offset:3072
	v_add_u32_e32 v200, s2, v32
	v_min_u32_e32 v200, 0x7ffe, v200
	v_mov_b32_e32 v201, 0
	v_lshlrev_b64 v[202:203], 12, v[200:201]
	v_lshl_add_u64 v[202:203], v[28:29], 0, v[202:203]
	global_load_dwordx4 v[204:207], v[202:203], off
	global_load_dwordx4 v[208:211], v[202:203], off offset:1024
	global_load_dwordx4 v[212:215], v[202:203], off offset:2048
	global_load_dwordx4 v[216:219], v[202:203], off offset:3072
	v_add_co_u32_e32 v202, vcc, 0x1000, v202
	s_nop 1
	v_addc_co_u32_e32 v203, vcc, 0, v203, vcc
	global_load_dwordx4 v[220:223], v[202:203], off
	global_load_dwordx4 v[224:227], v[202:203], off offset:1024
	global_load_dwordx4 v[228:231], v[202:203], off offset:2048
	global_load_dwordx4 v[232:235], v[202:203], off offset:3072
	s_cmpk_lt_i32 s4, 0x1000
	s_waitcnt vmcnt(15)
	v_mov_b32_e32 v60, v39
	s_waitcnt vmcnt(14)
	v_mov_b32_e32 v61, v43
	s_waitcnt vmcnt(13)
	v_mov_b32_e32 v68, v47
	s_waitcnt vmcnt(12)
	v_mov_b32_e32 v69, v51
	v_mov_b32_e32 v58, v38
	v_mov_b32_e32 v59, v42
	v_mov_b32_e32 v66, v46
	v_mov_b32_e32 v67, v50
	v_pk_mul_f32 v[60:61], v[60:61], v[60:61]
	v_pk_mul_f32 v[68:69], v[68:69], v[68:69]
	v_mov_b32_e32 v62, v40
	v_mov_b32_e32 v63, v44
	v_pk_fma_f32 v[58:59], v[58:59], v[58:59], v[60:61]
	v_pk_fma_f32 v[60:61], v[66:67], v[66:67], v[68:69]
	s_waitcnt vmcnt(11)
	v_mov_b32_e32 v68, v55
	s_waitcnt vmcnt(10)
	v_mov_b32_e32 v69, v25
	v_mov_b32_e32 v66, v54
	v_mov_b32_e32 v67, v24
	s_waitcnt vmcnt(9)
	v_mov_b32_e32 v80, v21
	s_waitcnt vmcnt(8)
	v_mov_b32_e32 v81, v17
	v_pk_fma_f32 v[58:59], v[62:63], v[62:63], v[58:59]
	v_pk_mul_f32 v[62:63], v[68:69], v[68:69]
	v_mov_b32_e32 v64, v41
	v_mov_b32_e32 v65, v45
	v_mov_b32_e32 v74, v56
	v_mov_b32_e32 v75, v26
	v_mov_b32_e32 v78, v20
	v_mov_b32_e32 v79, v16
	v_pk_mul_f32 v[68:69], v[80:81], v[80:81]
	v_pk_fma_f32 v[62:63], v[66:67], v[66:67], v[62:63]
	v_mov_b32_e32 v70, v48
	v_mov_b32_e32 v71, v52
	v_mov_b32_e32 v76, v57
	v_mov_b32_e32 v77, v27
	v_mov_b32_e32 v82, v22
	v_mov_b32_e32 v83, v18
	v_pk_fma_f32 v[58:59], v[64:65], v[64:65], v[58:59]
	v_pk_fma_f32 v[64:65], v[78:79], v[78:79], v[68:69]
	v_pk_fma_f32 v[62:63], v[74:75], v[74:75], v[62:63]
	v_mov_b32_e32 v72, v49
	v_mov_b32_e32 v73, v53
	v_mov_b32_e32 v84, v23
	v_mov_b32_e32 v85, v19
	v_pk_fma_f32 v[60:61], v[70:71], v[70:71], v[60:61]
	v_pk_fma_f32 v[64:65], v[82:83], v[82:83], v[64:65]
	v_pk_fma_f32 v[62:63], v[76:77], v[76:77], v[62:63]
	v_pk_fma_f32 v[60:61], v[72:73], v[72:73], v[60:61]
	v_mov_b32_e32 v67, v58
	v_pk_fma_f32 v[64:65], v[84:85], v[84:85], v[64:65]
	v_mov_b32_e32 v66, v62
	v_mov_b32_e32 v58, v63
	v_mov_b32_e32 v69, v60
	v_mov_b32_e32 v68, v64
	v_pk_add_f32 v[58:59], v[66:67], v[58:59]
	v_mov_b32_e32 v60, v65
	v_pk_add_f32 v[58:59], v[58:59], v[68:69]
	s_nop 0
	v_pk_add_f32 v[58:59], v[58:59], v[60:61]
	s_nop 1
	v_mov_b32_dpp v61, v59 quad_perm:[1,0,3,2] row_mask:0xf bank_mask:0xf bound_ctrl:1
	v_mov_b32_dpp v60, v58 quad_perm:[1,0,3,2] row_mask:0xf bank_mask:0xf bound_ctrl:1
	v_pk_add_f32 v[58:59], v[58:59], v[60:61]
	s_nop 1
	v_mov_b32_dpp v61, v59 quad_perm:[2,3,0,1] row_mask:0xf bank_mask:0xf bound_ctrl:1
	v_mov_b32_dpp v60, v58 quad_perm:[2,3,0,1] row_mask:0xf bank_mask:0xf bound_ctrl:1
	v_pk_add_f32 v[58:59], v[58:59], v[60:61]
	s_nop 1
	v_mov_b32_dpp v61, v59 row_half_mirror row_mask:0xf bank_mask:0xf bound_ctrl:1
	v_mov_b32_dpp v60, v58 row_half_mirror row_mask:0xf bank_mask:0xf bound_ctrl:1
	v_pk_add_f32 v[58:59], v[58:59], v[60:61]
	s_nop 1
	v_mov_b32_dpp v61, v59 row_mirror row_mask:0xf bank_mask:0xf bound_ctrl:1
	v_mov_b32_dpp v60, v58 row_mirror row_mask:0xf bank_mask:0xf bound_ctrl:1
	v_pk_add_f32 v[58:59], v[58:59], v[60:61]
	ds_bpermute_b32 v61, v36, v59
	ds_bpermute_b32 v60, v36, v58
	s_waitcnt lgkmcnt(0)
; DI unsigned pack2(float lo, float hi) { const f32x2c v = {lo, hi}; return __builtin_bit_cast(unsigned, __builtin_convertvector(v, bf16x2c)); }
; DI void phase_rmsnorm(const Ctx& c, const float* src, const float* w) {
;     ...
;       ss = wave_sum(ss);
;       const float rs = rsqrtf(ss * (1.0f / 1024.0f) + 1e-5f);
;       bf16_t* o = xn + (size_t)(row + r) * 1024;
; #pragma unroll
;       for (int i = 0; i < 4; ++i) { u32x2 q; q.x = pack2(v[r][i][0] * rs * g[i][0], v[r][i][1] * rs * g[i][1]); q.y = pack2(v[r][i][2] * rs * g[i][2], v[r][i][3] * rs * g[i][3]); *(u32x2*)(o + i * 256 + lane * 4) = q; }
;     }
	v_pk_add_f32 v[58:59], v[58:59], v[60:61]
	ds_bpermute_b32 v61, v37, v59
	ds_bpermute_b32 v60, v37, v58
	s_waitcnt lgkmcnt(0)
	v_pk_add_f32 v[58:59], v[58:59], v[60:61]
	s_nop 0
	v_pk_fma_f32 v[58:59], v[58:59], s[0:1], v[34:35] op_sel_hi:[1,0,0]
	s_nop 0
	v_mul_f32_e32 v60, 0x4b800000, v59
	v_cmp_gt_f32_e32 vcc, s3, v59
	s_nop 1
	v_cndmask_b32_e32 v59, v59, v60, vcc
	v_rsq_f32_e32 v59, v59
	v_lshlrev_b64 v[60:61], 11, v[32:33]
	v_mul_f32_e32 v33, 0x4b800000, v58
	v_lshl_add_u64 v[60:61], v[30:31], 0, v[60:61]
	v_mul_f32_e32 v62, 0x45800000, v59
	v_cndmask_b32_e32 v62, v59, v62, vcc
	v_cmp_gt_f32_e32 vcc, s3, v58
	v_pk_mul_f32 v[38:39], v[38:39], v[62:63] op_sel_hi:[1,0]
	v_pk_mul_f32 v[40:41], v[40:41], v[62:63] op_sel_hi:[1,0]
	v_cndmask_b32_e32 v33, v58, v33, vcc
	v_rsq_f32_e32 v33, v33
	v_pk_mul_f32 v[42:43], v[42:43], v[62:63] op_sel_hi:[1,0]
	v_pk_mul_f32 v[44:45], v[44:45], v[62:63] op_sel_hi:[1,0]
	v_pk_mul_f32 v[46:47], v[46:47], v[62:63] op_sel_hi:[1,0]
	v_pk_mul_f32 v[48:49], v[48:49], v[62:63] op_sel_hi:[1,0]
	v_pk_mul_f32 v[38:39], v[12:13], v[38:39]
	v_pk_mul_f32 v[40:41], v[14:15], v[40:41]
	v_pk_mul_f32 v[52:53], v[52:53], v[62:63] op_sel_hi:[1,0]
	v_pk_mul_f32 v[42:43], v[4:5], v[42:43]
	v_pk_mul_f32 v[44:45], v[6:7], v[44:45]
	v_pk_mul_f32 v[46:47], v[0:1], v[46:47]
	v_pk_mul_f32 v[48:49], v[2:3], v[48:49]
	v_cvt_pk_bf16_f32 v38, v38, v39
	v_cvt_pk_bf16_f32 v39, v40, v41
	v_pk_mul_f32 v[50:51], v[50:51], v[62:63] op_sel_hi:[1,0]
	v_cvt_pk_bf16_f32 v40, v42, v43
	v_cvt_pk_bf16_f32 v41, v44, v45
	v_cvt_pk_bf16_f32 v42, v46, v47
	v_cvt_pk_bf16_f32 v43, v48, v49
	global_store_dwordx2 v[60:61], v[38:39], off
	global_store_dwordx2 v[60:61], v[40:41], off offset:512
	global_store_dwordx2 v[60:61], v[42:43], off offset:1024
	v_pk_mul_f32 v[38:39], v[10:11], v[52:53]
	v_pk_mul_f32 v[50:51], v[8:9], v[50:51]
	v_cvt_pk_bf16_f32 v45, v38, v39
	v_mul_f32_e32 v38, 0x45800000, v33
	v_cvt_pk_bf16_f32 v44, v50, v51
	v_cndmask_b32_e32 v38, v33, v38, vcc
	v_add_u32_e32 v40, 1, v32
	global_store_dwordx2 v[60:61], v[44:45], off offset:1536
	v_ashrrev_i32_e32 v41, 31, v40
	v_pk_mul_f32 v[42:43], v[54:55], v[38:39] op_sel_hi:[1,0]
	v_pk_mul_f32 v[44:45], v[56:57], v[38:39] op_sel_hi:[1,0]
	v_pk_mul_f32 v[24:25], v[24:25], v[38:39] op_sel_hi:[1,0]
	v_pk_mul_f32 v[26:27], v[26:27], v[38:39] op_sel_hi:[1,0]
	v_pk_mul_f32 v[20:21], v[20:21], v[38:39] op_sel_hi:[1,0]
	v_pk_mul_f32 v[22:23], v[22:23], v[38:39] op_sel_hi:[1,0]
	v_pk_mul_f32 v[16:17], v[16:17], v[38:39] op_sel_hi:[1,0]
	v_pk_mul_f32 v[18:19], v[18:19], v[38:39] op_sel_hi:[1,0]
	v_lshlrev_b64 v[40:41], 11, v[40:41]
	v_pk_mul_f32 v[42:43], v[12:13], v[42:43]
	v_pk_mul_f32 v[44:45], v[14:15], v[44:45]
	v_pk_mul_f32 v[24:25], v[4:5], v[24:25]
	v_pk_mul_f32 v[26:27], v[6:7], v[26:27]
	v_pk_mul_f32 v[20:21], v[0:1], v[20:21]
	v_pk_mul_f32 v[22:23], v[2:3], v[22:23]
	v_pk_mul_f32 v[16:17], v[8:9], v[16:17]
	v_pk_mul_f32 v[18:19], v[10:11], v[18:19]
	v_lshl_add_u64 v[40:41], v[30:31], 0, v[40:41]
	v_cvt_pk_bf16_f32 v42, v42, v43
	v_cvt_pk_bf16_f32 v43, v44, v45
	v_cvt_pk_bf16_f32 v24, v24, v25
	v_cvt_pk_bf16_f32 v25, v26, v27
	v_cvt_pk_bf16_f32 v20, v20, v21
	v_cvt_pk_bf16_f32 v21, v22, v23
	v_cvt_pk_bf16_f32 v16, v16, v17
	v_cvt_pk_bf16_f32 v17, v18, v19
	v_add_u32_e32 v32, s2, v32
	global_store_dwordx2 v[40:41], v[42:43], off
	global_store_dwordx2 v[40:41], v[24:25], off offset:512
	global_store_dwordx2 v[40:41], v[20:21], off offset:1024
	global_store_dwordx2 v[40:41], v[16:17], off offset:1536
	s_cbranch_scc1 .LBB0_960

; DI void phase_rmsnorm(const Ctx& c, const float* src, const float* w) {
;     ...
;   for (int u = blockIdx.x; u < NTOK / 8; u += gridDim.x) {
;     const int row = u * 8 + wid * 2;
;     const float* xr = src + (size_t)row * 1024;
;     f32x4 v[2][4];
; #pragma unroll
;     for (int r = 0; r < 2; ++r)
; #pragma unroll
;       for (int i = 0; i < 4; ++i) v[r][i] = *(const f32x4*)(xr + r * 1024 + i * 256 + lane * 4);
; #pragma unroll
;     for (int r = 0; r < 2; ++r) {
;       float ss = 0.f;
; #pragma unroll
;       for (int i = 0; i < 4; ++i) ss += v[r][i][0] * v[r][i][0] + v[r][i][1] * v[r][i][1] + v[r][i][2] * v[r][i][2] + v[r][i][3] * v[r][i][3];
;       ss = wave_sum(ss);
.LBB0_1875:
	v_ashrrev_i32_e32 v33, 31, v32
	v_lshlrev_b64 v[16:17], 12, v[32:33]
	v_lshl_add_u64 v[16:17], v[28:29], 0, v[16:17]
	global_load_dwordx4 v[38:41], v[16:17], off
	global_load_dwordx4 v[42:45], v[16:17], off offset:1024
	global_load_dwordx4 v[46:49], v[16:17], off offset:2048
	global_load_dwordx4 v[50:53], v[16:17], off offset:3072
	v_add_co_u32_e32 v58, vcc, 0x1000, v16
	s_add_i32 s4, s4, s1
	s_nop 0
	v_addc_co_u32_e32 v59, vcc, 0, v17, vcc
	global_load_dwordx4 v[54:57], v[58:59], off
	global_load_dwordx4 v[24:27], v[58:59], off offset:1024
	global_load_dwordx4 v[20:23], v[58:59], off offset:2048
	global_load_dwordx4 v[16:19], v[58:59], off offset:3072
	v_add_u32_e32 v200, s2, v32
	v_min_u32_e32 v200, 0x7ffe, v200
	v_mov_b32_e32 v201, 0
	v_lshlrev_b64 v[202:203], 12, v[200:201]
	v_lshl_add_u64 v[202:203], v[28:29], 0, v[202:203]
	global_load_dwordx4 v[204:207], v[202:203], off
	global_load_dwordx4 v[208:211], v[202:203], off offset:1024
	global_load_dwordx4 v[212:215], v[202:203], off offset:2048
	global_load_dwordx4 v[216:219], v[202:203], off offset:3072
	v_add_co_u32_e32 v202, vcc, 0x1000, v202
	s_nop 1
	v_addc_co_u32_e32 v203, vcc, 0, v203, vcc
	global_load_dwordx4 v[220:223], v[202:203], off
	global_load_dwordx4 v[224:227], v[202:203], off offset:1024
	global_load_dwordx4 v[228:231], v[202:203], off offset:2048
	global_load_dwordx4 v[232:235], v[202:203], off offset:3072
	s_cmpk_lt_i32 s4, 0x1000
	s_waitcnt vmcnt(15)
	v_mov_b32_e32 v60, v39
	s_waitcnt vmcnt(14)
	v_mov_b32_e32 v61, v43
	s_waitcnt vmcnt(13)
	v_mov_b32_e32 v68, v47
	s_waitcnt vmcnt(12)
	v_mov_b32_e32 v69, v51
	v_mov_b32_e32 v58, v38
	v_mov_b32_e32 v59, v42
	v_mov_b32_e32 v66, v46
	v_mov_b32_e32 v67, v50
	v_pk_mul_f32 v[60:61], v[60:61], v[60:61]
	v_pk_mul_f32 v[68:69], v[68:69], v[68:69]
	v_mov_b32_e32 v62, v40
	v_mov_b32_e32 v63, v44
	v_pk_fma_f32 v[58:59], v[58:59], v[58:59], v[60:61]
	v_pk_fma_f32 v[60:61], v[66:67], v[66:67], v[68:69]
	s_waitcnt vmcnt(11)
	v_mov_b32_e32 v68, v55
	s_waitcnt vmcnt(10)
	v_mov_b32_e32 v69, v25
	v_mov_b32_e32 v66, v54
	v_mov_b32_e32 v67, v24
	s_waitcnt vmcnt(9)
	v_mov_b32_e32 v80, v21
	s_waitcnt vmcnt(8)
	v_mov_b32_e32 v81, v17
	v_pk_fma_f32 v[58:59], v[62:63], v[62:63], v[58:59]
	v_pk_mul_f32 v[62:63], v[68:69], v[68:69]
	v_mov_b32_e32 v64, v41
	v_mov_b32_e32 v65, v45
	v_mov_b32_e32 v74, v56
	v_mov_b32_e32 v75, v26
	v_mov_b32_e32 v78, v20
	v_mov_b32_e32 v79, v16
	v_pk_mul_f32 v[68:69], v[80:81], v[80:81]
	v_pk_fma_f32 v[62:63], v[66:67], v[66:67], v[62:63]
	v_mov_b32_e32 v70, v48
	v_mov_b32_e32 v71, v52
	v_mov_b32_e32 v76, v57
	v_mov_b32_e32 v77, v27
	v_mov_b32_e32 v82, v22
	v_mov_b32_e32 v83, v18
	v_pk_fma_f32 v[58:59], v[64:65], v[64:65], v[58:59]
	v_pk_fma_f32 v[64:65], v[78:79], v[78:79], v[68:69]
	v_pk_fma_f32 v[62:63], v[74:75], v[74:75], v[62:63]
	v_mov_b32_e32 v72, v49
	v_mov_b32_e32 v73, v53
	v_mov_b32_e32 v84, v23
	v_mov_b32_e32 v85, v19
	v_pk_fma_f32 v[60:61], v[70:71], v[70:71], v[60:61]
	v_pk_fma_f32 v[64:65], v[82:83], v[82:83], v[64:65]
	v_pk_fma_f32 v[62:63], v[76:77], v[76:77], v[62:63]
	v_pk_fma_f32 v[60:61], v[72:73], v[72:73], v[60:61]
	v_mov_b32_e32 v67, v58
	v_pk_fma_f32 v[64:65], v[84:85], v[84:85], v[64:65]
	v_mov_b32_e32 v66, v62
	v_mov_b32_e32 v58, v63
	v_mov_b32_e32 v69, v60
	v_mov_b32_e32 v68, v64
	v_pk_add_f32 v[58:59], v[66:67], v[58:59]
	v_mov_b32_e32 v60, v65
	v_pk_add_f32 v[58:59], v[58:59], v[68:69]
	s_nop 0
	v_pk_add_f32 v[58:59], v[58:59], v[60:61]
	s_nop 1
	v_mov_b32_dpp v61, v59 quad_perm:[1,0,3,2] row_mask:0xf bank_mask:0xf bound_ctrl:1
	v_mov_b32_dpp v60, v58 quad_perm:[1,0,3,2] row_mask:0xf bank_mask:0xf bound_ctrl:1
	v_pk_add_f32 v[58:59], v[58:59], v[60:61]
	s_nop 1
	v_mov_b32_dpp v61, v59 quad_perm:[2,3,0,1] row_mask:0xf bank_mask:0xf bound_ctrl:1
	v_mov_b32_dpp v60, v58 quad_perm:[2,3,0,1] row_mask:0xf bank_mask:0xf bound_ctrl:1
	v_pk_add_f32 v[58:59], v[58:59], v[60:61]
	s_nop 1
	v_mov_b32_dpp v61, v59 row_half_mirror row_mask:0xf bank_mask:0xf bound_ctrl:1
	v_mov_b32_dpp v60, v58 row_half_mirror row_mask:0xf bank_mask:0xf bound_ctrl:1
	v_pk_add_f32 v[58:59], v[58:59], v[60:61]
	s_nop 1
	v_mov_b32_dpp v61, v59 row_mirror row_mask:0xf bank_mask:0xf bound_ctrl:1
	v_mov_b32_dpp v60, v58 row_mirror row_mask:0xf bank_mask:0xf bound_ctrl:1
	v_pk_add_f32 v[58:59], v[58:59], v[60:61]
	ds_bpermute_b32 v61, v36, v59
	ds_bpermute_b32 v60, v36, v58
	s_waitcnt lgkmcnt(0)
; DI unsigned pack2(float lo, float hi) { const f32x2c v = {lo, hi}; return __builtin_bit_cast(unsigned, __builtin_convertvector(v, bf16x2c)); }
; DI void phase_rmsnorm(const Ctx& c, const float* src, const float* w) {
;     ...
;       ss = wave_sum(ss);
;       const float rs = rsqrtf(ss * (1.0f / 1024.0f) + 1e-5f);
;       bf16_t* o = xn + (size_t)(row + r) * 1024;
; #pragma unroll
;       for (int i = 0; i < 4; ++i) { u32x2 q; q.x = pack2(v[r][i][0] * rs * g[i][0], v[r][i][1] * rs * g[i][1]); q.y = pack2(v[r][i][2] * rs * g[i][2], v[r][i][3] * rs * g[i][3]); *(u32x2*)(o + i * 256 + lane * 4) = q; }
;     }
	v_pk_add_f32 v[58:59], v[58:59], v[60:61]
	ds_bpermute_b32 v61, v37, v59
	ds_bpermute_b32 v60, v37, v58
	s_waitcnt lgkmcnt(0)
	v_pk_add_f32 v[58:59], v[58:59], v[60:61]
	s_nop 0
	v_pk_fma_f32 v[58:59], v[58:59], s[0:1], v[34:35] op_sel_hi:[1,0,0]
	s_nop 0
	v_mul_f32_e32 v60, 0x4b800000, v59
	v_cmp_gt_f32_e32 vcc, s3, v59
	s_nop 1
	v_cndmask_b32_e32 v59, v59, v60, vcc
	v_rsq_f32_e32 v59, v59
	v_lshlrev_b64 v[60:61], 11, v[32:33]
	v_mul_f32_e32 v33, 0x4b800000, v58
	v_lshl_add_u64 v[60:61], v[30:31], 0, v[60:61]
	v_mul_f32_e32 v62, 0x45800000, v59
	v_cndmask_b32_e32 v62, v59, v62, vcc
	v_cmp_gt_f32_e32 vcc, s3, v58
	v_pk_mul_f32 v[38:39], v[38:39], v[62:63] op_sel_hi:[1,0]
	v_pk_mul_f32 v[40:41], v[40:41], v[62:63] op_sel_hi:[1,0]
	v_cndmask_b32_e32 v33, v58, v33, vcc
	v_rsq_f32_e32 v33, v33
	v_pk_mul_f32 v[42:43], v[42:43], v[62:63] op_sel_hi:[1,0]
	v_pk_mul_f32 v[44:45], v[44:45], v[62:63] op_sel_hi:[1,0]
	v_pk_mul_f32 v[46:47], v[46:47], v[62:63] op_sel_hi:[1,0]
	v_pk_mul_f32 v[48:49], v[48:49], v[62:63] op_sel_hi:[1,0]
	v_pk_mul_f32 v[38:39], v[12:13], v[38:39]
	v_pk_mul_f32 v[40:41], v[14:15], v[40:41]
	v_pk_mul_f32 v[52:53], v[52:53], v[62:63] op_sel_hi:[1,0]
	v_pk_mul_f32 v[42:43], v[4:5], v[42:43]
	v_pk_mul_f32 v[44:45], v[6:7], v[44:45]
	v_pk_mul_f32 v[46:47], v[0:1], v[46:47]
	v_pk_mul_f32 v[48:49], v[2:3], v[48:49]
	v_cvt_pk_bf16_f32 v38, v38, v39
	v_cvt_pk_bf16_f32 v39, v40, v41
	v_pk_mul_f32 v[50:51], v[50:51], v[62:63] op_sel_hi:[1,0]
	v_cvt_pk_bf16_f32 v40, v42, v43
	v_cvt_pk_bf16_f32 v41, v44, v45
	v_cvt_pk_bf16_f32 v42, v46, v47
	v_cvt_pk_bf16_f32 v43, v48, v49
	global_store_dwordx2 v[60:61], v[38:39], off
	global_store_dwordx2 v[60:61], v[40:41], off offset:512
	global_store_dwordx2 v[60:61], v[42:43], off offset:1024
	v_pk_mul_f32 v[38:39], v[10:11], v[52:53]
	v_pk_mul_f32 v[50:51], v[8:9], v[50:51]
	v_cvt_pk_bf16_f32 v45, v38, v39
	v_mul_f32_e32 v38, 0x45800000, v33
	v_cvt_pk_bf16_f32 v44, v50, v51
	v_cndmask_b32_e32 v38, v33, v38, vcc
	v_add_u32_e32 v40, 1, v32
	global_store_dwordx2 v[60:61], v[44:45], off offset:1536
	v_ashrrev_i32_e32 v41, 31, v40
	v_pk_mul_f32 v[42:43], v[54:55], v[38:39] op_sel_hi:[1,0]
	v_pk_mul_f32 v[44:45], v[56:57], v[38:39] op_sel_hi:[1,0]
	v_pk_mul_f32 v[24:25], v[24:25], v[38:39] op_sel_hi:[1,0]
	v_pk_mul_f32 v[26:27], v[26:27], v[38:39] op_sel_hi:[1,0]
	v_pk_mul_f32 v[20:21], v[20:21], v[38:39] op_sel_hi:[1,0]
	v_pk_mul_f32 v[22:23], v[22:23], v[38:39] op_sel_hi:[1,0]
	v_pk_mul_f32 v[16:17], v[16:17], v[38:39] op_sel_hi:[1,0]
	v_pk_mul_f32 v[18:19], v[18:19], v[38:39] op_sel_hi:[1,0]
	v_lshlrev_b64 v[40:41], 11, v[40:41]
	v_pk_mul_f32 v[42:43], v[12:13], v[42:43]
	v_pk_mul_f32 v[44:45], v[14:15], v[44:45]
	v_pk_mul_f32 v[24:25], v[4:5], v[24:25]
	v_pk_mul_f32 v[26:27], v[6:7], v[26:27]
	v_pk_mul_f32 v[20:21], v[0:1], v[20:21]
	v_pk_mul_f32 v[22:23], v[2:3], v[22:23]
	v_pk_mul_f32 v[16:17], v[8:9], v[16:17]
	v_pk_mul_f32 v[18:19], v[10:11], v[18:19]
	v_lshl_add_u64 v[40:41], v[30:31], 0, v[40:41]
	v_cvt_pk_bf16_f32 v42, v42, v43
	v_cvt_pk_bf16_f32 v43, v44, v45
	v_cvt_pk_bf16_f32 v24, v24, v25
	v_cvt_pk_bf16_f32 v25, v26, v27
	v_cvt_pk_bf16_f32 v20, v20, v21
	v_cvt_pk_bf16_f32 v21, v22, v23
	v_cvt_pk_bf16_f32 v16, v16, v17
	v_cvt_pk_bf16_f32 v17, v18, v19
	v_add_u32_e32 v32, s2, v32
	global_store_dwordx2 v[40:41], v[42:43], off
	global_store_dwordx2 v[40:41], v[24:25], off offset:512
	global_store_dwordx2 v[40:41], v[20:21], off offset:1024
	global_store_dwordx2 v[40:41], v[16:17], off offset:1536
	s_cbranch_scc1 .LBB0_1875

; DI void phase_final(const Ctx& c) {
;     ...
;   for (int u = blockIdx.x; u < NTOK / 8; u += gridDim.x) {
;     float* xr = p.out + (size_t)(u * 8 + wid * 2) * 1024;
;     f32x4 v[2][4];
; #pragma unroll
;     for (int r = 0; r < 2; ++r)
; #pragma unroll
;       for (int i = 0; i < 4; ++i) v[r][i] = *(const f32x4*)(xr + r * 1024 + i * 256 + lane * 4);
; #pragma unroll
;     for (int r = 0; r < 2; ++r) {
;       float ss = 0.f;
; #pragma unroll
;       for (int i = 0; i < 4; ++i) ss += v[r][i][0] * v[r][i][0] + v[r][i][1] * v[r][i][1] + v[r][i][2] * v[r][i][2] + v[r][i][3] * v[r][i][3];
;       ss = wave_sum(ss);
.LBB0_1949:
	v_ashrrev_i32_e32 v19, 31, v18
	v_lshlrev_b64 v[22:23], 12, v[18:19]
	v_lshl_add_u64 v[58:59], v[16:17], 0, v[22:23]
	global_load_dwordx4 v[26:29], v[58:59], off
	global_load_dwordx4 v[30:33], v[58:59], off offset:1024
	global_load_dwordx4 v[34:37], v[58:59], off offset:2048
	global_load_dwordx4 v[38:41], v[58:59], off offset:3072
	v_add_co_u32_e32 v22, vcc, 0x1000, v58
	s_add_i32 s6, s6, s1
	s_nop 0
	v_addc_co_u32_e32 v23, vcc, 0, v59, vcc
	global_load_dwordx4 v[42:45], v[22:23], off
	global_load_dwordx4 v[46:49], v[22:23], off offset:1024
	global_load_dwordx4 v[50:53], v[22:23], off offset:2048
	global_load_dwordx4 v[54:57], v[22:23], off offset:3072
	v_add_u32_e32 v200, s4, v18
	v_min_u32_e32 v200, 0x7ffe, v200
	v_mov_b32_e32 v201, 0
	v_lshlrev_b64 v[202:203], 12, v[200:201]
	v_lshl_add_u64 v[202:203], v[16:17], 0, v[202:203]
	global_load_dwordx4 v[204:207], v[202:203], off
	global_load_dwordx4 v[208:211], v[202:203], off offset:1024
	global_load_dwordx4 v[212:215], v[202:203], off offset:2048
	global_load_dwordx4 v[216:219], v[202:203], off offset:3072
	v_add_co_u32_e32 v202, vcc, 0x1000, v202
	s_nop 1
	v_addc_co_u32_e32 v203, vcc, 0, v203, vcc
	global_load_dwordx4 v[220:223], v[202:203], off
	global_load_dwordx4 v[224:227], v[202:203], off offset:1024
	global_load_dwordx4 v[228:231], v[202:203], off offset:2048
	global_load_dwordx4 v[232:235], v[202:203], off offset:3072
	s_cmpk_lt_i32 s6, 0x1000
	v_add_u32_e32 v18, s4, v18
	s_waitcnt vmcnt(15)
	v_mov_b32_e32 v62, v27
	s_waitcnt vmcnt(14)
	v_mov_b32_e32 v63, v31
	s_waitcnt vmcnt(13)
	v_mov_b32_e32 v70, v35
	s_waitcnt vmcnt(12)
	v_mov_b32_e32 v71, v39
	v_mov_b32_e32 v60, v26
	v_mov_b32_e32 v61, v30
	v_mov_b32_e32 v68, v34
	v_mov_b32_e32 v69, v38
	v_pk_mul_f32 v[62:63], v[62:63], v[62:63]
	v_pk_mul_f32 v[70:71], v[70:71], v[70:71]
	v_mov_b32_e32 v64, v28
	v_mov_b32_e32 v65, v32
	v_pk_fma_f32 v[60:61], v[60:61], v[60:61], v[62:63]
	v_pk_fma_f32 v[62:63], v[68:69], v[68:69], v[70:71]
	s_waitcnt vmcnt(11)
	v_mov_b32_e32 v70, v43
	s_waitcnt vmcnt(10)
	v_mov_b32_e32 v71, v47
	v_mov_b32_e32 v68, v42
	v_mov_b32_e32 v69, v46
	s_waitcnt vmcnt(9)
	v_mov_b32_e32 v82, v51
	s_waitcnt vmcnt(8)
	v_mov_b32_e32 v83, v55
	v_pk_fma_f32 v[60:61], v[64:65], v[64:65], v[60:61]
	v_pk_mul_f32 v[64:65], v[70:71], v[70:71]
	v_mov_b32_e32 v66, v29
	v_mov_b32_e32 v67, v33
	v_mov_b32_e32 v76, v44
	v_mov_b32_e32 v77, v48
	v_mov_b32_e32 v80, v50
	v_mov_b32_e32 v81, v54
	v_pk_mul_f32 v[70:71], v[82:83], v[82:83]
	v_pk_fma_f32 v[64:65], v[68:69], v[68:69], v[64:65]
	v_mov_b32_e32 v72, v36
	v_mov_b32_e32 v73, v40
	v_mov_b32_e32 v78, v45
	v_mov_b32_e32 v79, v49
	v_mov_b32_e32 v84, v52
	v_mov_b32_e32 v85, v56
	v_pk_fma_f32 v[60:61], v[66:67], v[66:67], v[60:61]
	v_pk_fma_f32 v[66:67], v[80:81], v[80:81], v[70:71]
	v_pk_fma_f32 v[64:65], v[76:77], v[76:77], v[64:65]
	v_mov_b32_e32 v74, v37
	v_mov_b32_e32 v75, v41
	v_mov_b32_e32 v86, v53
	v_mov_b32_e32 v87, v57
	v_pk_fma_f32 v[62:63], v[72:73], v[72:73], v[62:63]
	v_pk_fma_f32 v[66:67], v[84:85], v[84:85], v[66:67]
	v_pk_fma_f32 v[64:65], v[78:79], v[78:79], v[64:65]
	v_pk_fma_f32 v[62:63], v[74:75], v[74:75], v[62:63]
	v_mov_b32_e32 v69, v60
	v_pk_fma_f32 v[66:67], v[86:87], v[86:87], v[66:67]
	v_mov_b32_e32 v68, v64
	v_mov_b32_e32 v60, v65
	v_mov_b32_e32 v71, v62
	v_mov_b32_e32 v70, v66
	v_pk_add_f32 v[60:61], v[68:69], v[60:61]
	v_mov_b32_e32 v62, v67
	v_pk_add_f32 v[60:61], v[60:61], v[70:71]
	s_nop 0
	v_pk_add_f32 v[60:61], v[60:61], v[62:63]
	s_nop 1
	v_mov_b32_dpp v63, v61 quad_perm:[1,0,3,2] row_mask:0xf bank_mask:0xf bound_ctrl:1
	v_mov_b32_dpp v62, v60 quad_perm:[1,0,3,2] row_mask:0xf bank_mask:0xf bound_ctrl:1
	v_pk_add_f32 v[60:61], v[60:61], v[62:63]
	s_nop 1
	v_mov_b32_dpp v63, v61 quad_perm:[2,3,0,1] row_mask:0xf bank_mask:0xf bound_ctrl:1
	v_mov_b32_dpp v62, v60 quad_perm:[2,3,0,1] row_mask:0xf bank_mask:0xf bound_ctrl:1
	v_pk_add_f32 v[60:61], v[60:61], v[62:63]
	s_nop 1
	v_mov_b32_dpp v63, v61 row_half_mirror row_mask:0xf bank_mask:0xf bound_ctrl:1
	v_mov_b32_dpp v62, v60 row_half_mirror row_mask:0xf bank_mask:0xf bound_ctrl:1
	v_pk_add_f32 v[60:61], v[60:61], v[62:63]
	s_nop 1
	v_mov_b32_dpp v63, v61 row_mirror row_mask:0xf bank_mask:0xf bound_ctrl:1
	v_mov_b32_dpp v62, v60 row_mirror row_mask:0xf bank_mask:0xf bound_ctrl:1
	v_pk_add_f32 v[60:61], v[60:61], v[62:63]
	ds_bpermute_b32 v63, v24, v61
	ds_bpermute_b32 v62, v24, v60
	s_waitcnt lgkmcnt(0)
; DI void phase_final(const Ctx& c) {
;     ...
;       ss = wave_sum(ss);
;       const float rs = rsqrtf(ss * (1.0f / 1024.0f) + 1e-5f);
; #pragma unroll
;       for (int i = 0; i < 4; ++i) *(f32x4*)(xr + r * 1024 + i * 256 + lane * 4) = v[r][i] * rs * g[i];
	v_pk_add_f32 v[60:61], v[60:61], v[62:63]
	ds_bpermute_b32 v63, v25, v61
	ds_bpermute_b32 v62, v25, v60
	s_waitcnt lgkmcnt(0)
	v_pk_add_f32 v[60:61], v[60:61], v[62:63]
	s_nop 0
	v_pk_fma_f32 v[60:61], v[60:61], s[0:1], v[20:21] op_sel_hi:[1,0,0]
	s_nop 0
	v_mul_f32_e32 v19, 0x4b800000, v61
	v_cmp_gt_f32_e32 vcc, s5, v61
	v_mul_f32_e32 v62, 0x4b800000, v60
	v_cmp_gt_f32_e64 s[2:3], s5, v60
	v_cndmask_b32_e32 v19, v61, v19, vcc
	v_rsq_f32_e32 v19, v19
	v_cndmask_b32_e64 v60, v60, v62, s[2:3]
	v_rsq_f32_e32 v61, v60
	v_mul_f32_e32 v60, 0x45800000, v19
	v_cndmask_b32_e32 v60, v19, v60, vcc
	v_mul_f32_e32 v62, 0x45800000, v61
	v_cndmask_b32_e64 v62, v61, v62, s[2:3]
	v_pk_mul_f32 v[26:27], v[26:27], v[60:61] op_sel_hi:[1,0]
	v_pk_mul_f32 v[28:29], v[28:29], v[60:61] op_sel_hi:[1,0]
	v_pk_mul_f32 v[30:31], v[30:31], v[60:61] op_sel_hi:[1,0]
	v_pk_mul_f32 v[32:33], v[32:33], v[60:61] op_sel_hi:[1,0]
	v_pk_mul_f32 v[34:35], v[34:35], v[60:61] op_sel_hi:[1,0]
	v_pk_mul_f32 v[36:37], v[36:37], v[60:61] op_sel_hi:[1,0]
	v_pk_mul_f32 v[38:39], v[38:39], v[60:61] op_sel_hi:[1,0]
	v_pk_mul_f32 v[40:41], v[40:41], v[60:61] op_sel_hi:[1,0]
	v_pk_mul_f32 v[42:43], v[42:43], v[62:63] op_sel_hi:[1,0]
	v_pk_mul_f32 v[44:45], v[44:45], v[62:63] op_sel_hi:[1,0]
	v_pk_mul_f32 v[28:29], v[2:3], v[28:29]
	v_pk_mul_f32 v[26:27], v[0:1], v[26:27]
	v_pk_mul_f32 v[32:33], v[6:7], v[32:33]
	v_pk_mul_f32 v[30:31], v[4:5], v[30:31]
	v_pk_mul_f32 v[36:37], v[10:11], v[36:37]
	v_pk_mul_f32 v[34:35], v[8:9], v[34:35]
	v_pk_mul_f32 v[40:41], v[14:15], v[40:41]
	v_pk_mul_f32 v[38:39], v[12:13], v[38:39]
	global_store_dwordx4 v[58:59], v[26:29], off
	global_store_dwordx4 v[58:59], v[30:33], off offset:1024
	global_store_dwordx4 v[58:59], v[34:37], off offset:2048
	global_store_dwordx4 v[58:59], v[38:41], off offset:3072
	v_pk_mul_f32 v[28:29], v[2:3], v[44:45]
	v_pk_mul_f32 v[26:27], v[0:1], v[42:43]
	global_store_dwordx4 v[22:23], v[26:29], off
	s_nop 1
	v_pk_mul_f32 v[26:27], v[46:47], v[62:63] op_sel_hi:[1,0]
	v_pk_mul_f32 v[28:29], v[48:49], v[62:63] op_sel_hi:[1,0]
	v_pk_mul_f32 v[26:27], v[4:5], v[26:27]
	v_pk_mul_f32 v[28:29], v[6:7], v[28:29]
	global_store_dwordx4 v[22:23], v[26:29], off offset:1024
	s_nop 1
	v_pk_mul_f32 v[26:27], v[50:51], v[62:63] op_sel_hi:[1,0]
	v_pk_mul_f32 v[28:29], v[52:53], v[62:63] op_sel_hi:[1,0]
	v_pk_mul_f32 v[26:27], v[8:9], v[26:27]
	v_pk_mul_f32 v[28:29], v[10:11], v[28:29]
	global_store_dwordx4 v[22:23], v[26:29], off offset:2048
	s_nop 1
	v_pk_mul_f32 v[26:27], v[54:55], v[62:63] op_sel_hi:[1,0]
	v_pk_mul_f32 v[28:29], v[56:57], v[62:63] op_sel_hi:[1,0]
	v_pk_mul_f32 v[26:27], v[12:13], v[26:27]
	v_pk_mul_f32 v[28:29], v[14:15], v[28:29]
	global_store_dwordx4 v[22:23], v[26:29], off offset:3072
	s_cbranch_scc1 .LBB0_1949
